# scan publish: HP rows staged as an LDS image and stored with wide write-through (sc1) stores, so the release needs no L2 write-back before the flag
# speedup vs baseline: 1.0026x; 1.0026x over previous
; #define LAS __attribute__((address_space(3)))
; #define S5_LOAD(SR, SI, cb) do { _Pragma("unroll") for (int i = 0; i < 16; ++i) { SR[i] = sc[(size_t)((cb) + i) * 128 + n]; SI[i] = sc[(size_t)((cb) + i) * 128 + 64 + n]; } } while (0)
; #define S5_STEP(SR, SI, cb) do { _Pragma("unroll") for (int i = 0; i < 16; ++i) { \
;         hp[(size_t)((cb) + i) * 128 + n] = (bf16)f2bf(hr); hp[(size_t)((cb) + i) * 128 + 64 + n] = (bf16)f2bf(hi); \
;         const float nhr = atr * hr - ati * hi + SR[i], nhi = atr * hi + ati * hr + SI[i]; hr = nhr; hi = nhi; } } while (0)
; __device__ __forceinline__ void s5_scan_block(LAS unsigned char* lds, const Args& a, const float* __restrict__ SC, bf16* HP, int g, int wave, int lane) {
;     ...
;     const float* sc = SC + ((size_t)g * SNC + c0) * 128; bf16* hp = HP + ((size_t)g * SNC + c0) * 128;
;     LAS float* ex = (LAS float*)lds;
;     float sr0[16], si0[16];
;     ...
;     for (int cb = 0; cb < 64; cb += 16) { S5_LOAD(sr0, si0, cb); S5_STEP(sr0, si0, cb); }
.LBB0_777:
	s_lshl_b64 s[0:1], s[66:67], 17
	s_lshl_b64 s[2:3], s[4:5], 8
	s_add_u32 s0, s0, s2
	s_addc_u32 s1, s1, s3
	v_lshl_or_b32 v10, v184, 1, s0
	v_mov_b32_e32 v11, s1
	s_mov_b64 s[0:1], 0x19c00800
	v_lshl_add_u64 v[10:11], v[10:11], 0, s[0:1]
	s_lshl_b64 s[0:1], s[66:67], 18
	s_lshl_b64 s[2:3], s[4:5], 9
	s_add_u32 s0, s0, s2
	s_addc_u32 s1, s1, s3
	v_mov_b32_e32 v3, v2
	v_mov_b32_e32 v1, v0
	v_mov_b32_e32 v6, v2
	v_mov_b32_e32 v7, v0
	v_mov_b32_e32 v8, v0
	v_mov_b32_e32 v9, v2
	v_lshl_or_b32 v12, v184, 2, s0
	v_mov_b32_e32 v13, s1
	s_movk_i32 s9, 0x7fff
	s_mov_b64 s[2:3], 0x1000
	v_lshl_add_u64 v[14:15], s[88:89], 0, v[10:11]
	s_waitcnt vmcnt(0)
	s_lshl_b32 s6, s4, 8
	s_add_i32 s6, s6, 0x1000
	v_lshl_add_u32 v28, v184, 1, s6
	v_lshl_add_u32 v29, v184, 4, s6
	v_bfe_u32 v20, v4, 16, 1
	v_bfe_u32 v21, v5, 16, 1
	v_mul_f32_e32 v22, v0, v5
	v_mul_f32_e32 v23, v0, v4
	v_add3_u32 v20, v4, v20, s9
	v_add3_u32 v21, v5, v21, s9
	v_fma_f32 v22, v2, v4, -v22
	v_fma_f32 v23, v2, v5, v23
	ds_write_b16_d16_hi v28, v20
	ds_write_b16_d16_hi v28, v21 offset:128
	v_add_f32_e32 v4, v22, v64
	v_add_f32_e32 v5, v23, v65
	v_bfe_u32 v24, v4, 16, 1
	v_bfe_u32 v25, v5, 16, 1
	v_mul_f32_e32 v26, v0, v5
	v_mul_f32_e32 v27, v0, v4
	v_add3_u32 v24, v4, v24, s9
	v_add3_u32 v25, v5, v25, s9
	v_fma_f32 v26, v2, v4, -v26
	v_fma_f32 v27, v2, v5, v27
	ds_write_b16_d16_hi v28, v24 offset:256
	ds_write_b16_d16_hi v28, v25 offset:384
	v_add_f32_e32 v4, v26, v66
	v_add_f32_e32 v5, v27, v67
	v_bfe_u32 v20, v4, 16, 1
	v_bfe_u32 v21, v5, 16, 1
	v_mul_f32_e32 v22, v0, v5
	v_mul_f32_e32 v23, v0, v4
	v_add3_u32 v20, v4, v20, s9
	v_add3_u32 v21, v5, v21, s9
	v_fma_f32 v22, v2, v4, -v22
	v_fma_f32 v23, v2, v5, v23
	ds_write_b16_d16_hi v28, v20 offset:512
	ds_write_b16_d16_hi v28, v21 offset:640
	v_add_f32_e32 v4, v22, v68
	v_add_f32_e32 v5, v23, v69
	v_bfe_u32 v24, v4, 16, 1
	v_bfe_u32 v25, v5, 16, 1
	v_mul_f32_e32 v26, v0, v5
	v_mul_f32_e32 v27, v0, v4
	v_add3_u32 v24, v4, v24, s9
	v_add3_u32 v25, v5, v25, s9
	v_fma_f32 v26, v2, v4, -v26
	v_fma_f32 v27, v2, v5, v27
	ds_write_b16_d16_hi v28, v24 offset:768
	ds_write_b16_d16_hi v28, v25 offset:896
	v_add_f32_e32 v4, v26, v70
	v_add_f32_e32 v5, v27, v71
	v_bfe_u32 v20, v4, 16, 1
	v_bfe_u32 v21, v5, 16, 1
	v_mul_f32_e32 v22, v0, v5
	v_mul_f32_e32 v23, v0, v4
	v_add3_u32 v20, v4, v20, s9
	v_add3_u32 v21, v5, v21, s9
	v_fma_f32 v22, v2, v4, -v22
	v_fma_f32 v23, v2, v5, v23
	ds_write_b16_d16_hi v28, v20 offset:1024
	ds_write_b16_d16_hi v28, v21 offset:1152
	v_add_f32_e32 v4, v22, v72
	v_add_f32_e32 v5, v23, v73
	v_bfe_u32 v24, v4, 16, 1
	v_bfe_u32 v25, v5, 16, 1
	v_mul_f32_e32 v26, v0, v5
	v_mul_f32_e32 v27, v0, v4
	v_add3_u32 v24, v4, v24, s9
	v_add3_u32 v25, v5, v25, s9
	v_fma_f32 v26, v2, v4, -v26
	v_fma_f32 v27, v2, v5, v27
	ds_write_b16_d16_hi v28, v24 offset:1280
	ds_write_b16_d16_hi v28, v25 offset:1408
	v_add_f32_e32 v4, v26, v74
	v_add_f32_e32 v5, v27, v75
	v_bfe_u32 v20, v4, 16, 1
	v_bfe_u32 v21, v5, 16, 1
	v_mul_f32_e32 v22, v0, v5
	v_mul_f32_e32 v23, v0, v4
	v_add3_u32 v20, v4, v20, s9
	v_add3_u32 v21, v5, v21, s9
	v_fma_f32 v22, v2, v4, -v22
	v_fma_f32 v23, v2, v5, v23
	ds_write_b16_d16_hi v28, v20 offset:1536
	ds_write_b16_d16_hi v28, v21 offset:1664
	v_add_f32_e32 v4, v22, v76
	v_add_f32_e32 v5, v23, v77
	v_bfe_u32 v24, v4, 16, 1
	v_bfe_u32 v25, v5, 16, 1
	v_mul_f32_e32 v26, v0, v5
	v_mul_f32_e32 v27, v0, v4
	v_add3_u32 v24, v4, v24, s9
	v_add3_u32 v25, v5, v25, s9
	v_fma_f32 v26, v2, v4, -v26
	v_fma_f32 v27, v2, v5, v27
	ds_write_b16_d16_hi v28, v24 offset:1792
	ds_write_b16_d16_hi v28, v25 offset:1920
	v_add_f32_e32 v4, v26, v78
	v_add_f32_e32 v5, v27, v79
	v_bfe_u32 v20, v4, 16, 1
	v_bfe_u32 v21, v5, 16, 1
	v_mul_f32_e32 v22, v0, v5
	v_mul_f32_e32 v23, v0, v4
	v_add3_u32 v20, v4, v20, s9
	v_add3_u32 v21, v5, v21, s9
	v_fma_f32 v22, v2, v4, -v22
	v_fma_f32 v23, v2, v5, v23
	ds_write_b16_d16_hi v28, v20 offset:2048
	ds_write_b16_d16_hi v28, v21 offset:2176
	v_add_f32_e32 v4, v22, v80
	v_add_f32_e32 v5, v23, v81
	v_bfe_u32 v24, v4, 16, 1
	v_bfe_u32 v25, v5, 16, 1
	v_mul_f32_e32 v26, v0, v5
	v_mul_f32_e32 v27, v0, v4
	v_add3_u32 v24, v4, v24, s9
	v_add3_u32 v25, v5, v25, s9
	v_fma_f32 v26, v2, v4, -v26
	v_fma_f32 v27, v2, v5, v27
	ds_write_b16_d16_hi v28, v24 offset:2304
	ds_write_b16_d16_hi v28, v25 offset:2432
	v_add_f32_e32 v4, v26, v82
	v_add_f32_e32 v5, v27, v83
	v_bfe_u32 v20, v4, 16, 1
	v_bfe_u32 v21, v5, 16, 1
	v_mul_f32_e32 v22, v0, v5
	v_mul_f32_e32 v23, v0, v4
	v_add3_u32 v20, v4, v20, s9
	v_add3_u32 v21, v5, v21, s9
	v_fma_f32 v22, v2, v4, -v22
	v_fma_f32 v23, v2, v5, v23
	ds_write_b16_d16_hi v28, v20 offset:2560
	ds_write_b16_d16_hi v28, v21 offset:2688
	v_add_f32_e32 v4, v22, v84
	v_add_f32_e32 v5, v23, v85
	v_bfe_u32 v24, v4, 16, 1
	v_bfe_u32 v25, v5, 16, 1
	v_mul_f32_e32 v26, v0, v5
	v_mul_f32_e32 v27, v0, v4
	v_add3_u32 v24, v4, v24, s9
	v_add3_u32 v25, v5, v25, s9
	v_fma_f32 v26, v2, v4, -v26
	v_fma_f32 v27, v2, v5, v27
	ds_write_b16_d16_hi v28, v24 offset:2816
	ds_write_b16_d16_hi v28, v25 offset:2944
	v_add_f32_e32 v4, v26, v86
	v_add_f32_e32 v5, v27, v87
	v_bfe_u32 v20, v4, 16, 1
	v_bfe_u32 v21, v5, 16, 1
	v_mul_f32_e32 v22, v0, v5
	v_mul_f32_e32 v23, v0, v4
	v_add3_u32 v20, v4, v20, s9
	v_add3_u32 v21, v5, v21, s9
	v_fma_f32 v22, v2, v4, -v22
	v_fma_f32 v23, v2, v5, v23
	ds_write_b16_d16_hi v28, v20 offset:3072
	ds_write_b16_d16_hi v28, v21 offset:3200
	v_add_f32_e32 v4, v22, v88
	v_add_f32_e32 v5, v23, v89
	v_bfe_u32 v24, v4, 16, 1
	v_bfe_u32 v25, v5, 16, 1
	v_mul_f32_e32 v26, v0, v5
	v_mul_f32_e32 v27, v0, v4
	v_add3_u32 v24, v4, v24, s9
	v_add3_u32 v25, v5, v25, s9
	v_fma_f32 v26, v2, v4, -v26
; #define S5_LOAD(SR, SI, cb) do { _Pragma("unroll") for (int i = 0; i < 16; ++i) { SR[i] = sc[(size_t)((cb) + i) * 128 + n]; SI[i] = sc[(size_t)((cb) + i) * 128 + 64 + n]; } } while (0)
; #define S5_STEP(SR, SI, cb) do { _Pragma("unroll") for (int i = 0; i < 16; ++i) { \
;         hp[(size_t)((cb) + i) * 128 + n] = (bf16)f2bf(hr); hp[(size_t)((cb) + i) * 128 + 64 + n] = (bf16)f2bf(hi); \
;         const float nhr = atr * hr - ati * hi + SR[i], nhi = atr * hi + ati * hr + SI[i]; hr = nhr; hi = nhi; } } while (0)
; __device__ __forceinline__ void s5_scan_block(LAS unsigned char* lds, const Args& a, const float* __restrict__ SC, bf16* HP, int g, int wave, int lane) {
;     ...
;     for (int cb = 0; cb < 64; cb += 16) { S5_LOAD(sr0, si0, cb); S5_STEP(sr0, si0, cb); }
	v_fma_f32 v27, v2, v5, v27
	ds_write_b16_d16_hi v28, v24 offset:3328
	ds_write_b16_d16_hi v28, v25 offset:3456
	v_add_f32_e32 v4, v26, v90
	v_add_f32_e32 v5, v27, v91
	v_bfe_u32 v20, v4, 16, 1
	v_bfe_u32 v21, v5, 16, 1
	v_mul_f32_e32 v22, v0, v5
	v_mul_f32_e32 v23, v0, v4
	v_add3_u32 v20, v4, v20, s9
	v_add3_u32 v21, v5, v21, s9
	v_fma_f32 v22, v2, v4, -v22
	v_fma_f32 v23, v2, v5, v23
	ds_write_b16_d16_hi v28, v20 offset:3584
	ds_write_b16_d16_hi v28, v21 offset:3712
	v_add_f32_e32 v4, v22, v92
	v_add_f32_e32 v5, v23, v93
	v_bfe_u32 v24, v4, 16, 1
	v_bfe_u32 v25, v5, 16, 1
	v_mul_f32_e32 v26, v0, v5
	v_mul_f32_e32 v27, v0, v4
	v_add3_u32 v24, v4, v24, s9
	v_add3_u32 v25, v5, v25, s9
	v_fma_f32 v26, v2, v4, -v26
	v_fma_f32 v27, v2, v5, v27
	ds_write_b16_d16_hi v28, v24 offset:3840
	ds_write_b16_d16_hi v28, v25 offset:3968
	v_add_f32_e32 v4, v26, v94
	v_add_f32_e32 v5, v27, v95
	v_bfe_u32 v20, v4, 16, 1
	v_bfe_u32 v21, v5, 16, 1
	v_mul_f32_e32 v22, v0, v5
	v_mul_f32_e32 v23, v0, v4
	v_add3_u32 v20, v4, v20, s9
	v_add3_u32 v21, v5, v21, s9
	v_fma_f32 v22, v2, v4, -v22
	v_fma_f32 v23, v2, v5, v23
	ds_write_b16_d16_hi v28, v20 offset:4096
	ds_write_b16_d16_hi v28, v21 offset:4224
	v_add_f32_e32 v4, v22, v96
	v_add_f32_e32 v5, v23, v97
	v_bfe_u32 v24, v4, 16, 1
	v_bfe_u32 v25, v5, 16, 1
	v_mul_f32_e32 v26, v0, v5
	v_mul_f32_e32 v27, v0, v4
	v_add3_u32 v24, v4, v24, s9
	v_add3_u32 v25, v5, v25, s9
	v_fma_f32 v26, v2, v4, -v26
	v_fma_f32 v27, v2, v5, v27
	ds_write_b16_d16_hi v28, v24 offset:4352
	ds_write_b16_d16_hi v28, v25 offset:4480
	v_add_f32_e32 v4, v26, v98
	v_add_f32_e32 v5, v27, v99
	v_bfe_u32 v20, v4, 16, 1
	v_bfe_u32 v21, v5, 16, 1
	v_mul_f32_e32 v22, v0, v5
	v_mul_f32_e32 v23, v0, v4
	v_add3_u32 v20, v4, v20, s9
	v_add3_u32 v21, v5, v21, s9
	v_fma_f32 v22, v2, v4, -v22
	v_fma_f32 v23, v2, v5, v23
	ds_write_b16_d16_hi v28, v20 offset:4608
	ds_write_b16_d16_hi v28, v21 offset:4736
	v_add_f32_e32 v4, v22, v100
	v_add_f32_e32 v5, v23, v101
	v_bfe_u32 v24, v4, 16, 1
	v_bfe_u32 v25, v5, 16, 1
	v_mul_f32_e32 v26, v0, v5
	v_mul_f32_e32 v27, v0, v4
	v_add3_u32 v24, v4, v24, s9
	v_add3_u32 v25, v5, v25, s9
	v_fma_f32 v26, v2, v4, -v26
	v_fma_f32 v27, v2, v5, v27
	ds_write_b16_d16_hi v28, v24 offset:4864
	ds_write_b16_d16_hi v28, v25 offset:4992
	v_add_f32_e32 v4, v26, v102
	v_add_f32_e32 v5, v27, v103
	v_bfe_u32 v20, v4, 16, 1
	v_bfe_u32 v21, v5, 16, 1
	v_mul_f32_e32 v22, v0, v5
	v_mul_f32_e32 v23, v0, v4
	v_add3_u32 v20, v4, v20, s9
	v_add3_u32 v21, v5, v21, s9
	v_fma_f32 v22, v2, v4, -v22
	v_fma_f32 v23, v2, v5, v23
	ds_write_b16_d16_hi v28, v20 offset:5120
	ds_write_b16_d16_hi v28, v21 offset:5248
	v_add_f32_e32 v4, v22, v104
	v_add_f32_e32 v5, v23, v105
	v_bfe_u32 v24, v4, 16, 1
	v_bfe_u32 v25, v5, 16, 1
	v_mul_f32_e32 v26, v0, v5
	v_mul_f32_e32 v27, v0, v4
	v_add3_u32 v24, v4, v24, s9
	v_add3_u32 v25, v5, v25, s9
	v_fma_f32 v26, v2, v4, -v26
	v_fma_f32 v27, v2, v5, v27
	ds_write_b16_d16_hi v28, v24 offset:5376
	ds_write_b16_d16_hi v28, v25 offset:5504
	v_add_f32_e32 v4, v26, v106
	v_add_f32_e32 v5, v27, v107
	v_bfe_u32 v20, v4, 16, 1
	v_bfe_u32 v21, v5, 16, 1
	v_mul_f32_e32 v22, v0, v5
	v_mul_f32_e32 v23, v0, v4
	v_add3_u32 v20, v4, v20, s9
	v_add3_u32 v21, v5, v21, s9
	v_fma_f32 v22, v2, v4, -v22
	v_fma_f32 v23, v2, v5, v23
	ds_write_b16_d16_hi v28, v20 offset:5632
	ds_write_b16_d16_hi v28, v21 offset:5760
	v_add_f32_e32 v4, v22, v108
	v_add_f32_e32 v5, v23, v109
	v_bfe_u32 v24, v4, 16, 1
	v_bfe_u32 v25, v5, 16, 1
	v_mul_f32_e32 v26, v0, v5
	v_mul_f32_e32 v27, v0, v4
	v_add3_u32 v24, v4, v24, s9
	v_add3_u32 v25, v5, v25, s9
	v_fma_f32 v26, v2, v4, -v26
	v_fma_f32 v27, v2, v5, v27
	ds_write_b16_d16_hi v28, v24 offset:5888
	ds_write_b16_d16_hi v28, v25 offset:6016
	v_add_f32_e32 v4, v26, v110
	v_add_f32_e32 v5, v27, v111
	v_bfe_u32 v20, v4, 16, 1
	v_bfe_u32 v21, v5, 16, 1
	v_mul_f32_e32 v22, v0, v5
	v_mul_f32_e32 v23, v0, v4
	v_add3_u32 v20, v4, v20, s9
	v_add3_u32 v21, v5, v21, s9
	v_fma_f32 v22, v2, v4, -v22
	v_fma_f32 v23, v2, v5, v23
	ds_write_b16_d16_hi v28, v20 offset:6144
	ds_write_b16_d16_hi v28, v21 offset:6272
	v_add_f32_e32 v4, v22, v112
	v_add_f32_e32 v5, v23, v113
	v_bfe_u32 v24, v4, 16, 1
	v_bfe_u32 v25, v5, 16, 1
	v_mul_f32_e32 v26, v0, v5
	v_mul_f32_e32 v27, v0, v4
	v_add3_u32 v24, v4, v24, s9
	v_add3_u32 v25, v5, v25, s9
	v_fma_f32 v26, v2, v4, -v26
	v_fma_f32 v27, v2, v5, v27
	ds_write_b16_d16_hi v28, v24 offset:6400
	ds_write_b16_d16_hi v28, v25 offset:6528
	v_add_f32_e32 v4, v26, v114
	v_add_f32_e32 v5, v27, v115
	v_bfe_u32 v20, v4, 16, 1
	v_bfe_u32 v21, v5, 16, 1
	v_mul_f32_e32 v22, v0, v5
	v_mul_f32_e32 v23, v0, v4
	v_add3_u32 v20, v4, v20, s9
	v_add3_u32 v21, v5, v21, s9
	v_fma_f32 v22, v2, v4, -v22
	v_fma_f32 v23, v2, v5, v23
	ds_write_b16_d16_hi v28, v20 offset:6656
	ds_write_b16_d16_hi v28, v21 offset:6784
	v_add_f32_e32 v4, v22, v116
	v_add_f32_e32 v5, v23, v117
	v_bfe_u32 v24, v4, 16, 1
	v_bfe_u32 v25, v5, 16, 1
	v_mul_f32_e32 v26, v0, v5
	v_mul_f32_e32 v27, v0, v4
	v_add3_u32 v24, v4, v24, s9
	v_add3_u32 v25, v5, v25, s9
	v_fma_f32 v26, v2, v4, -v26
	v_fma_f32 v27, v2, v5, v27
	ds_write_b16_d16_hi v28, v24 offset:6912
	ds_write_b16_d16_hi v28, v25 offset:7040
	v_add_f32_e32 v4, v26, v118
	v_add_f32_e32 v5, v27, v119
	v_bfe_u32 v20, v4, 16, 1
	v_bfe_u32 v21, v5, 16, 1
	v_mul_f32_e32 v22, v0, v5
	v_mul_f32_e32 v23, v0, v4
	v_add3_u32 v20, v4, v20, s9
	v_add3_u32 v21, v5, v21, s9
	v_fma_f32 v22, v2, v4, -v22
	v_fma_f32 v23, v2, v5, v23
	ds_write_b16_d16_hi v28, v20 offset:7168
	ds_write_b16_d16_hi v28, v21 offset:7296
	v_add_f32_e32 v4, v22, v120
	v_add_f32_e32 v5, v23, v121
	v_bfe_u32 v24, v4, 16, 1
; #define S5_LOAD(SR, SI, cb) do { _Pragma("unroll") for (int i = 0; i < 16; ++i) { SR[i] = sc[(size_t)((cb) + i) * 128 + n]; SI[i] = sc[(size_t)((cb) + i) * 128 + 64 + n]; } } while (0)
; #define S5_STEP(SR, SI, cb) do { _Pragma("unroll") for (int i = 0; i < 16; ++i) { \
;         hp[(size_t)((cb) + i) * 128 + n] = (bf16)f2bf(hr); hp[(size_t)((cb) + i) * 128 + 64 + n] = (bf16)f2bf(hi); \
;         const float nhr = atr * hr - ati * hi + SR[i], nhi = atr * hi + ati * hr + SI[i]; hr = nhr; hi = nhi; } } while (0)
; __device__ __forceinline__ void s5_scan_block(LAS unsigned char* lds, const Args& a, const float* __restrict__ SC, bf16* HP, int g, int wave, int lane) {
;     ...
;     for (int cb = 0; cb < 64; cb += 16) { S5_LOAD(sr0, si0, cb); S5_STEP(sr0, si0, cb); }
	v_bfe_u32 v25, v5, 16, 1
	v_mul_f32_e32 v26, v0, v5
	v_mul_f32_e32 v27, v0, v4
	v_add3_u32 v24, v4, v24, s9
	v_add3_u32 v25, v5, v25, s9
	v_fma_f32 v26, v2, v4, -v26
	v_fma_f32 v27, v2, v5, v27
	ds_write_b16_d16_hi v28, v24 offset:7424
	ds_write_b16_d16_hi v28, v25 offset:7552
	v_add_f32_e32 v4, v26, v122
	v_add_f32_e32 v5, v27, v123
	v_bfe_u32 v20, v4, 16, 1
	v_bfe_u32 v21, v5, 16, 1
	v_mul_f32_e32 v22, v0, v5
	v_mul_f32_e32 v23, v0, v4
	v_add3_u32 v20, v4, v20, s9
	v_add3_u32 v21, v5, v21, s9
	v_fma_f32 v22, v2, v4, -v22
	v_fma_f32 v23, v2, v5, v23
	ds_write_b16_d16_hi v28, v20 offset:7680
	ds_write_b16_d16_hi v28, v21 offset:7808
	v_add_f32_e32 v4, v22, v124
	v_add_f32_e32 v5, v23, v125
	v_bfe_u32 v24, v4, 16, 1
	v_bfe_u32 v25, v5, 16, 1
	v_mul_f32_e32 v26, v0, v5
	v_mul_f32_e32 v27, v0, v4
	v_add3_u32 v24, v4, v24, s9
	v_add3_u32 v25, v5, v25, s9
	v_fma_f32 v26, v2, v4, -v26
	v_fma_f32 v27, v2, v5, v27
	ds_write_b16_d16_hi v28, v24 offset:7936
	ds_write_b16_d16_hi v28, v25 offset:8064
	v_add_f32_e32 v4, v26, v126
	v_add_f32_e32 v5, v27, v127
	v_bfe_u32 v20, v4, 16, 1
	v_bfe_u32 v21, v5, 16, 1
	v_mul_f32_e32 v22, v0, v5
	v_mul_f32_e32 v23, v0, v4
	v_add3_u32 v20, v4, v20, s9
	v_add3_u32 v21, v5, v21, s9
	v_fma_f32 v22, v2, v4, -v22
	v_fma_f32 v23, v2, v5, v23
	ds_write_b16_d16_hi v28, v20 offset:8192
	ds_write_b16_d16_hi v28, v21 offset:8320
	v_add_f32_e32 v4, v22, v128
	v_add_f32_e32 v5, v23, v129
	v_bfe_u32 v24, v4, 16, 1
	v_bfe_u32 v25, v5, 16, 1
	v_mul_f32_e32 v26, v0, v5
	v_mul_f32_e32 v27, v0, v4
	v_add3_u32 v24, v4, v24, s9
	v_add3_u32 v25, v5, v25, s9
	v_fma_f32 v26, v2, v4, -v26
	v_fma_f32 v27, v2, v5, v27
	ds_write_b16_d16_hi v28, v24 offset:8448
	ds_write_b16_d16_hi v28, v25 offset:8576
	v_add_f32_e32 v4, v26, v130
	v_add_f32_e32 v5, v27, v131
	v_bfe_u32 v20, v4, 16, 1
	v_bfe_u32 v21, v5, 16, 1
	v_mul_f32_e32 v22, v0, v5
	v_mul_f32_e32 v23, v0, v4
	v_add3_u32 v20, v4, v20, s9
	v_add3_u32 v21, v5, v21, s9
	v_fma_f32 v22, v2, v4, -v22
	v_fma_f32 v23, v2, v5, v23
	ds_write_b16_d16_hi v28, v20 offset:8704
	ds_write_b16_d16_hi v28, v21 offset:8832
	v_add_f32_e32 v4, v22, v132
	v_add_f32_e32 v5, v23, v133
	v_bfe_u32 v24, v4, 16, 1
	v_bfe_u32 v25, v5, 16, 1
	v_mul_f32_e32 v26, v0, v5
	v_mul_f32_e32 v27, v0, v4
	v_add3_u32 v24, v4, v24, s9
	v_add3_u32 v25, v5, v25, s9
	v_fma_f32 v26, v2, v4, -v26
	v_fma_f32 v27, v2, v5, v27
	ds_write_b16_d16_hi v28, v24 offset:8960
	ds_write_b16_d16_hi v28, v25 offset:9088
	v_add_f32_e32 v4, v26, v134
	v_add_f32_e32 v5, v27, v135
	v_bfe_u32 v20, v4, 16, 1
	v_bfe_u32 v21, v5, 16, 1
	v_mul_f32_e32 v22, v0, v5
	v_mul_f32_e32 v23, v0, v4
	v_add3_u32 v20, v4, v20, s9
	v_add3_u32 v21, v5, v21, s9
	v_fma_f32 v22, v2, v4, -v22
	v_fma_f32 v23, v2, v5, v23
	ds_write_b16_d16_hi v28, v20 offset:9216
	ds_write_b16_d16_hi v28, v21 offset:9344
	v_add_f32_e32 v4, v22, v136
	v_add_f32_e32 v5, v23, v137
	v_bfe_u32 v24, v4, 16, 1
	v_bfe_u32 v25, v5, 16, 1
	v_mul_f32_e32 v26, v0, v5
	v_mul_f32_e32 v27, v0, v4
	v_add3_u32 v24, v4, v24, s9
	v_add3_u32 v25, v5, v25, s9
	v_fma_f32 v26, v2, v4, -v26
	v_fma_f32 v27, v2, v5, v27
	ds_write_b16_d16_hi v28, v24 offset:9472
	ds_write_b16_d16_hi v28, v25 offset:9600
	v_add_f32_e32 v4, v26, v138
	v_add_f32_e32 v5, v27, v139
	v_bfe_u32 v20, v4, 16, 1
	v_bfe_u32 v21, v5, 16, 1
	v_mul_f32_e32 v22, v0, v5
	v_mul_f32_e32 v23, v0, v4
	v_add3_u32 v20, v4, v20, s9
	v_add3_u32 v21, v5, v21, s9
	v_fma_f32 v22, v2, v4, -v22
	v_fma_f32 v23, v2, v5, v23
	ds_write_b16_d16_hi v28, v20 offset:9728
	ds_write_b16_d16_hi v28, v21 offset:9856
	v_add_f32_e32 v4, v22, v140
	v_add_f32_e32 v5, v23, v141
	v_bfe_u32 v24, v4, 16, 1
	v_bfe_u32 v25, v5, 16, 1
	v_mul_f32_e32 v26, v0, v5
	v_mul_f32_e32 v27, v0, v4
	v_add3_u32 v24, v4, v24, s9
	v_add3_u32 v25, v5, v25, s9
	v_fma_f32 v26, v2, v4, -v26
	v_fma_f32 v27, v2, v5, v27
	ds_write_b16_d16_hi v28, v24 offset:9984
	ds_write_b16_d16_hi v28, v25 offset:10112
	v_add_f32_e32 v4, v26, v142
	v_add_f32_e32 v5, v27, v143
	v_bfe_u32 v20, v4, 16, 1
	v_bfe_u32 v21, v5, 16, 1
	v_mul_f32_e32 v22, v0, v5
	v_mul_f32_e32 v23, v0, v4
	v_add3_u32 v20, v4, v20, s9
	v_add3_u32 v21, v5, v21, s9
	v_fma_f32 v22, v2, v4, -v22
	v_fma_f32 v23, v2, v5, v23
	ds_write_b16_d16_hi v28, v20 offset:10240
	ds_write_b16_d16_hi v28, v21 offset:10368
	v_add_f32_e32 v4, v22, v144
	v_add_f32_e32 v5, v23, v145
	v_bfe_u32 v24, v4, 16, 1
	v_bfe_u32 v25, v5, 16, 1
	v_mul_f32_e32 v26, v0, v5
	v_mul_f32_e32 v27, v0, v4
	v_add3_u32 v24, v4, v24, s9
	v_add3_u32 v25, v5, v25, s9
	v_fma_f32 v26, v2, v4, -v26
	v_fma_f32 v27, v2, v5, v27
	ds_write_b16_d16_hi v28, v24 offset:10496
	ds_write_b16_d16_hi v28, v25 offset:10624
	v_add_f32_e32 v4, v26, v146
	v_add_f32_e32 v5, v27, v147
	v_bfe_u32 v20, v4, 16, 1
	v_bfe_u32 v21, v5, 16, 1
	v_mul_f32_e32 v22, v0, v5
	v_mul_f32_e32 v23, v0, v4
	v_add3_u32 v20, v4, v20, s9
	v_add3_u32 v21, v5, v21, s9
	v_fma_f32 v22, v2, v4, -v22
	v_fma_f32 v23, v2, v5, v23
	ds_write_b16_d16_hi v28, v20 offset:10752
	ds_write_b16_d16_hi v28, v21 offset:10880
	v_add_f32_e32 v4, v22, v148
	v_add_f32_e32 v5, v23, v149
	v_bfe_u32 v24, v4, 16, 1
	v_bfe_u32 v25, v5, 16, 1
	v_mul_f32_e32 v26, v0, v5
	v_mul_f32_e32 v27, v0, v4
	v_add3_u32 v24, v4, v24, s9
	v_add3_u32 v25, v5, v25, s9
	v_fma_f32 v26, v2, v4, -v26
	v_fma_f32 v27, v2, v5, v27
	ds_write_b16_d16_hi v28, v24 offset:11008
	ds_write_b16_d16_hi v28, v25 offset:11136
	v_add_f32_e32 v4, v26, v150
	v_add_f32_e32 v5, v27, v151
	v_bfe_u32 v20, v4, 16, 1
	v_bfe_u32 v21, v5, 16, 1
	v_mul_f32_e32 v22, v0, v5
	v_mul_f32_e32 v23, v0, v4
	v_add3_u32 v20, v4, v20, s9
	v_add3_u32 v21, v5, v21, s9
	v_fma_f32 v22, v2, v4, -v22
	v_fma_f32 v23, v2, v5, v23
; #define S5_LOAD(SR, SI, cb) do { _Pragma("unroll") for (int i = 0; i < 16; ++i) { SR[i] = sc[(size_t)((cb) + i) * 128 + n]; SI[i] = sc[(size_t)((cb) + i) * 128 + 64 + n]; } } while (0)
; #define S5_STEP(SR, SI, cb) do { _Pragma("unroll") for (int i = 0; i < 16; ++i) { \
;         hp[(size_t)((cb) + i) * 128 + n] = (bf16)f2bf(hr); hp[(size_t)((cb) + i) * 128 + 64 + n] = (bf16)f2bf(hi); \
;         const float nhr = atr * hr - ati * hi + SR[i], nhi = atr * hi + ati * hr + SI[i]; hr = nhr; hi = nhi; } } while (0)
; __device__ __forceinline__ void s5_scan_block(LAS unsigned char* lds, const Args& a, const float* __restrict__ SC, bf16* HP, int g, int wave, int lane) {
;     ...
;     for (int cb = 0; cb < 64; cb += 16) { S5_LOAD(sr0, si0, cb); S5_STEP(sr0, si0, cb); }
	ds_write_b16_d16_hi v28, v20 offset:11264
	ds_write_b16_d16_hi v28, v21 offset:11392
	v_add_f32_e32 v4, v22, v152
	v_add_f32_e32 v5, v23, v153
	v_bfe_u32 v24, v4, 16, 1
	v_bfe_u32 v25, v5, 16, 1
	v_mul_f32_e32 v26, v0, v5
	v_mul_f32_e32 v27, v0, v4
	v_add3_u32 v24, v4, v24, s9
	v_add3_u32 v25, v5, v25, s9
	v_fma_f32 v26, v2, v4, -v26
	v_fma_f32 v27, v2, v5, v27
	ds_write_b16_d16_hi v28, v24 offset:11520
	ds_write_b16_d16_hi v28, v25 offset:11648
	v_add_f32_e32 v4, v26, v154
	v_add_f32_e32 v5, v27, v155
	v_bfe_u32 v20, v4, 16, 1
	v_bfe_u32 v21, v5, 16, 1
	v_mul_f32_e32 v22, v0, v5
	v_mul_f32_e32 v23, v0, v4
	v_add3_u32 v20, v4, v20, s9
	v_add3_u32 v21, v5, v21, s9
	v_fma_f32 v22, v2, v4, -v22
	v_fma_f32 v23, v2, v5, v23
	ds_write_b16_d16_hi v28, v20 offset:11776
	ds_write_b16_d16_hi v28, v21 offset:11904
	v_add_f32_e32 v4, v22, v156
	v_add_f32_e32 v5, v23, v157
	v_bfe_u32 v24, v4, 16, 1
	v_bfe_u32 v25, v5, 16, 1
	v_mul_f32_e32 v26, v0, v5
	v_mul_f32_e32 v27, v0, v4
	v_add3_u32 v24, v4, v24, s9
	v_add3_u32 v25, v5, v25, s9
	v_fma_f32 v26, v2, v4, -v26
	v_fma_f32 v27, v2, v5, v27
	ds_write_b16_d16_hi v28, v24 offset:12032
	ds_write_b16_d16_hi v28, v25 offset:12160
	v_add_f32_e32 v4, v26, v158
	v_add_f32_e32 v5, v27, v159
	v_bfe_u32 v20, v4, 16, 1
	v_bfe_u32 v21, v5, 16, 1
	v_mul_f32_e32 v22, v0, v5
	v_mul_f32_e32 v23, v0, v4
	v_add3_u32 v20, v4, v20, s9
	v_add3_u32 v21, v5, v21, s9
	v_fma_f32 v22, v2, v4, -v22
	v_fma_f32 v23, v2, v5, v23
	ds_write_b16_d16_hi v28, v20 offset:12288
	ds_write_b16_d16_hi v28, v21 offset:12416
	v_add_f32_e32 v4, v22, v160
	v_add_f32_e32 v5, v23, v161
	v_bfe_u32 v24, v4, 16, 1
	v_bfe_u32 v25, v5, 16, 1
	v_mul_f32_e32 v26, v0, v5
	v_mul_f32_e32 v27, v0, v4
	v_add3_u32 v24, v4, v24, s9
	v_add3_u32 v25, v5, v25, s9
	v_fma_f32 v26, v2, v4, -v26
	v_fma_f32 v27, v2, v5, v27
	ds_write_b16_d16_hi v28, v24 offset:12544
	ds_write_b16_d16_hi v28, v25 offset:12672
	v_add_f32_e32 v4, v26, v162
	v_add_f32_e32 v5, v27, v163
	v_bfe_u32 v20, v4, 16, 1
	v_bfe_u32 v21, v5, 16, 1
	v_mul_f32_e32 v22, v0, v5
	v_mul_f32_e32 v23, v0, v4
	v_add3_u32 v20, v4, v20, s9
	v_add3_u32 v21, v5, v21, s9
	v_fma_f32 v22, v2, v4, -v22
	v_fma_f32 v23, v2, v5, v23
	ds_write_b16_d16_hi v28, v20 offset:12800
	ds_write_b16_d16_hi v28, v21 offset:12928
	v_add_f32_e32 v4, v22, v164
	v_add_f32_e32 v5, v23, v165
	v_bfe_u32 v24, v4, 16, 1
	v_bfe_u32 v25, v5, 16, 1
	v_mul_f32_e32 v26, v0, v5
	v_mul_f32_e32 v27, v0, v4
	v_add3_u32 v24, v4, v24, s9
	v_add3_u32 v25, v5, v25, s9
	v_fma_f32 v26, v2, v4, -v26
	v_fma_f32 v27, v2, v5, v27
	ds_write_b16_d16_hi v28, v24 offset:13056
	ds_write_b16_d16_hi v28, v25 offset:13184
	v_add_f32_e32 v4, v26, v166
	v_add_f32_e32 v5, v27, v167
	v_bfe_u32 v20, v4, 16, 1
	v_bfe_u32 v21, v5, 16, 1
	v_mul_f32_e32 v22, v0, v5
	v_mul_f32_e32 v23, v0, v4
	v_add3_u32 v20, v4, v20, s9
	v_add3_u32 v21, v5, v21, s9
	v_fma_f32 v22, v2, v4, -v22
	v_fma_f32 v23, v2, v5, v23
	ds_write_b16_d16_hi v28, v20 offset:13312
	ds_write_b16_d16_hi v28, v21 offset:13440
	v_add_f32_e32 v4, v22, v168
	v_add_f32_e32 v5, v23, v169
	v_bfe_u32 v24, v4, 16, 1
	v_bfe_u32 v25, v5, 16, 1
	v_mul_f32_e32 v26, v0, v5
	v_mul_f32_e32 v27, v0, v4
	v_add3_u32 v24, v4, v24, s9
	v_add3_u32 v25, v5, v25, s9
	v_fma_f32 v26, v2, v4, -v26
	v_fma_f32 v27, v2, v5, v27
	ds_write_b16_d16_hi v28, v24 offset:13568
	ds_write_b16_d16_hi v28, v25 offset:13696
	v_add_f32_e32 v4, v26, v170
	v_add_f32_e32 v5, v27, v171
	v_bfe_u32 v20, v4, 16, 1
	v_bfe_u32 v21, v5, 16, 1
	v_mul_f32_e32 v22, v0, v5
	v_mul_f32_e32 v23, v0, v4
	v_add3_u32 v20, v4, v20, s9
	v_add3_u32 v21, v5, v21, s9
	v_fma_f32 v22, v2, v4, -v22
	v_fma_f32 v23, v2, v5, v23
	ds_write_b16_d16_hi v28, v20 offset:13824
	ds_write_b16_d16_hi v28, v21 offset:13952
	v_add_f32_e32 v4, v22, v172
	v_add_f32_e32 v5, v23, v173
	v_bfe_u32 v24, v4, 16, 1
	v_bfe_u32 v25, v5, 16, 1
	v_mul_f32_e32 v26, v0, v5
	v_mul_f32_e32 v27, v0, v4
	v_add3_u32 v24, v4, v24, s9
	v_add3_u32 v25, v5, v25, s9
	v_fma_f32 v26, v2, v4, -v26
	v_fma_f32 v27, v2, v5, v27
	ds_write_b16_d16_hi v28, v24 offset:14080
	ds_write_b16_d16_hi v28, v25 offset:14208
	v_add_f32_e32 v4, v26, v174
	v_add_f32_e32 v5, v27, v175
	v_bfe_u32 v20, v4, 16, 1
	v_bfe_u32 v21, v5, 16, 1
	v_mul_f32_e32 v22, v0, v5
	v_mul_f32_e32 v23, v0, v4
	v_add3_u32 v20, v4, v20, s9
	v_add3_u32 v21, v5, v21, s9
	v_fma_f32 v22, v2, v4, -v22
	v_fma_f32 v23, v2, v5, v23
	ds_write_b16_d16_hi v28, v20 offset:14336
	ds_write_b16_d16_hi v28, v21 offset:14464
	v_add_f32_e32 v4, v22, v176
	v_add_f32_e32 v5, v23, v177
	v_bfe_u32 v24, v4, 16, 1
	v_bfe_u32 v25, v5, 16, 1
	v_mul_f32_e32 v26, v0, v5
	v_mul_f32_e32 v27, v0, v4
	v_add3_u32 v24, v4, v24, s9
	v_add3_u32 v25, v5, v25, s9
	v_fma_f32 v26, v2, v4, -v26
	v_fma_f32 v27, v2, v5, v27
	ds_write_b16_d16_hi v28, v24 offset:14592
	ds_write_b16_d16_hi v28, v25 offset:14720
	v_add_f32_e32 v4, v26, v178
	v_add_f32_e32 v5, v27, v179
; __global__ void __launch_bounds__(512, 2) mega(Args a) {
;     ...
;                 asm volatile("s_waitcnt vmcnt(0)" ::: "memory");
;                 __syncthreads();
;                 if (tid == 0) { __builtin_amdgcn_fence(__ATOMIC_RELEASE, "agent"); asm volatile("s_waitcnt vmcnt(0)" ::: "memory"); __hip_atomic_store(flg + 64 * b, 1u, __ATOMIC_RELAXED, __HIP_MEMORY_SCOPE_AGENT); }
	v_bfe_u32 v20, v4, 16, 1
	v_bfe_u32 v21, v5, 16, 1
	v_mul_f32_e32 v22, v0, v5
	v_mul_f32_e32 v23, v0, v4
	v_add3_u32 v20, v4, v20, s9
	v_add3_u32 v21, v5, v21, s9
	v_fma_f32 v22, v2, v4, -v22
	v_fma_f32 v23, v2, v5, v23
	ds_write_b16_d16_hi v28, v20 offset:14848
	ds_write_b16_d16_hi v28, v21 offset:14976
	v_add_f32_e32 v4, v22, v180
	v_add_f32_e32 v5, v23, v181
	v_bfe_u32 v24, v4, 16, 1
	v_bfe_u32 v25, v5, 16, 1
	v_mul_f32_e32 v26, v0, v5
	v_mul_f32_e32 v27, v0, v4
	v_add3_u32 v24, v4, v24, s9
	v_add3_u32 v25, v5, v25, s9
	v_fma_f32 v26, v2, v4, -v26
	v_fma_f32 v27, v2, v5, v27
	ds_write_b16_d16_hi v28, v24 offset:15104
	ds_write_b16_d16_hi v28, v25 offset:15232
	v_add_f32_e32 v4, v26, v182
	v_add_f32_e32 v5, v27, v183
	v_bfe_u32 v20, v4, 16, 1
	v_bfe_u32 v21, v5, 16, 1
	v_mul_f32_e32 v22, v0, v5
	v_mul_f32_e32 v23, v0, v4
	v_add3_u32 v20, v4, v20, s9
	v_add3_u32 v21, v5, v21, s9
	v_fma_f32 v22, v2, v4, -v22
	v_fma_f32 v23, v2, v5, v23
	ds_write_b16_d16_hi v28, v20 offset:15360
	ds_write_b16_d16_hi v28, v21 offset:15488
	v_add_f32_e32 v4, v22, v196
	v_add_f32_e32 v5, v23, v197
	v_bfe_u32 v24, v4, 16, 1
	v_bfe_u32 v25, v5, 16, 1
	v_mul_f32_e32 v26, v0, v5
	v_mul_f32_e32 v27, v0, v4
	v_add3_u32 v24, v4, v24, s9
	v_add3_u32 v25, v5, v25, s9
	v_fma_f32 v26, v2, v4, -v26
	v_fma_f32 v27, v2, v5, v27
	ds_write_b16_d16_hi v28, v24 offset:15616
	ds_write_b16_d16_hi v28, v25 offset:15744
	v_add_f32_e32 v4, v26, v198
	v_add_f32_e32 v5, v27, v199
	v_bfe_u32 v20, v4, 16, 1
	v_bfe_u32 v21, v5, 16, 1
	v_mul_f32_e32 v22, v0, v5
	v_mul_f32_e32 v23, v0, v4
	v_add3_u32 v20, v4, v20, s9
	v_add3_u32 v21, v5, v21, s9
	v_fma_f32 v22, v2, v4, -v22
	v_fma_f32 v23, v2, v5, v23
	ds_write_b16_d16_hi v28, v20 offset:15872
	ds_write_b16_d16_hi v28, v21 offset:16000
	v_add_f32_e32 v4, v22, v200
	v_add_f32_e32 v5, v23, v201
	v_bfe_u32 v24, v4, 16, 1
	v_bfe_u32 v25, v5, 16, 1
	v_mul_f32_e32 v26, v0, v5
	v_mul_f32_e32 v27, v0, v4
	v_add3_u32 v24, v4, v24, s9
	v_add3_u32 v25, v5, v25, s9
	v_fma_f32 v26, v2, v4, -v26
	v_fma_f32 v27, v2, v5, v27
	ds_write_b16_d16_hi v28, v24 offset:16128
	ds_write_b16_d16_hi v28, v25 offset:16256
	v_add_f32_e32 v4, v26, v202
	v_add_f32_e32 v5, v27, v203
	v_mul_u32_u24_e32 v30, 14, v184
	v_add_u32_e32 v30, 0xfffff800, v30
	v_add_co_u32_e32 v14, vcc, v30, v14
	s_nop 1
	v_addc_co_u32_e32 v15, vcc, -1, v15, vcc
	s_waitcnt lgkmcnt(0)
	ds_read_b128 v[64:67], v29
	ds_read_b128 v[68:71], v29 offset:1024
	ds_read_b128 v[72:75], v29 offset:2048
	ds_read_b128 v[76:79], v29 offset:3072
	ds_read_b128 v[80:83], v29 offset:4096
	ds_read_b128 v[84:87], v29 offset:5120
	ds_read_b128 v[88:91], v29 offset:6144
	ds_read_b128 v[92:95], v29 offset:7168
	ds_read_b128 v[96:99], v29 offset:8192
	ds_read_b128 v[100:103], v29 offset:9216
	ds_read_b128 v[104:107], v29 offset:10240
	ds_read_b128 v[108:111], v29 offset:11264
	ds_read_b128 v[112:115], v29 offset:12288
	ds_read_b128 v[116:119], v29 offset:13312
	ds_read_b128 v[120:123], v29 offset:14336
	ds_read_b128 v[124:127], v29 offset:15360
	s_waitcnt lgkmcnt(15)
	global_store_dwordx4 v[14:15], v[64:67], off sc1
	s_waitcnt lgkmcnt(14)
	global_store_dwordx4 v[14:15], v[68:71], off offset:1024 sc1
	s_waitcnt lgkmcnt(13)
	global_store_dwordx4 v[14:15], v[72:75], off offset:2048 sc1
	s_waitcnt lgkmcnt(12)
	global_store_dwordx4 v[14:15], v[76:79], off offset:3072 sc1
	v_lshl_add_u64 v[14:15], v[14:15], 0, s[2:3]
	s_waitcnt lgkmcnt(11)
	global_store_dwordx4 v[14:15], v[80:83], off sc1
	s_waitcnt lgkmcnt(10)
	global_store_dwordx4 v[14:15], v[84:87], off offset:1024 sc1
	s_waitcnt lgkmcnt(9)
	global_store_dwordx4 v[14:15], v[88:91], off offset:2048 sc1
	s_waitcnt lgkmcnt(8)
	global_store_dwordx4 v[14:15], v[92:95], off offset:3072 sc1
	v_lshl_add_u64 v[14:15], v[14:15], 0, s[2:3]
	s_waitcnt lgkmcnt(7)
	global_store_dwordx4 v[14:15], v[96:99], off sc1
	s_waitcnt lgkmcnt(6)
	global_store_dwordx4 v[14:15], v[100:103], off offset:1024 sc1
	s_waitcnt lgkmcnt(5)
	global_store_dwordx4 v[14:15], v[104:107], off offset:2048 sc1
	s_waitcnt lgkmcnt(4)
	global_store_dwordx4 v[14:15], v[108:111], off offset:3072 sc1
	v_lshl_add_u64 v[14:15], v[14:15], 0, s[2:3]
	s_waitcnt lgkmcnt(3)
	global_store_dwordx4 v[14:15], v[112:115], off sc1
	s_waitcnt lgkmcnt(2)
	global_store_dwordx4 v[14:15], v[116:119], off offset:1024 sc1
	s_waitcnt lgkmcnt(1)
	global_store_dwordx4 v[14:15], v[120:123], off offset:2048 sc1
	s_waitcnt lgkmcnt(0)
	global_store_dwordx4 v[14:15], v[124:127], off offset:3072 sc1
	s_waitcnt vmcnt(0)
	s_waitcnt lgkmcnt(0)
	s_barrier
	s_mov_b64 s[0:1], exec
	v_readlane_b32 s2, v245, 5
	v_readlane_b32 s3, v245, 6
	s_and_b64 s[2:3], s[0:1], s[2:3]
	s_mov_b64 exec, s[2:3]
	s_cbranch_execz .LBB0_781
	s_ashr_i32 s9, s8, 31
	s_lshl_b64 s[2:3], s[8:9], 2
	s_waitcnt vmcnt(0)
	s_waitcnt vmcnt(0)
	s_add_u32 s2, s24, s2
	s_addc_u32 s3, s25, s3
	v_mov_b32_e32 v0, 0
	v_mov_b32_e32 v1, 1
	global_store_dword v0, v1, s[2:3] sc1
